# v26: v25 + RG-LRU unit: gate-weight fragments requested with the raw tile; bias/lambda/state loads requested before the MFMAs (two serialized round trips removed)
# baseline (speedup 1.0000x reference)
; template <bool FINAL>
; DI void lru_unit(KA a, int l, int unit, LAS unsigned char* lds) {
;     ...
;     const bf16_t* U = (const bf16_t*)(a->ws + WS_HU);
;     LAS bf16_t* xc = (LAS bf16_t*)lds + w * (64 * 72);
;     LAS unsigned char* wsc = lds + 73728 + w * 8192;
;     LAS bf16_t* xr = (LAS bf16_t*)wsc;
;     const int row0 = u.row0, nvalid = u.nvalid;
;     const bool lastc = u.prompt ? (u.c == NCH - 1) : true;
;     float* out = a->out;
;     const bf16_t* WaT = (const bf16_t*)(a->ws + WS_WAT) + ((size_t)(l * 2 + 0) * 8 + w) * 4096;
;     const bf16_t* WxT = (const bf16_t*)(a->ws + WS_WAT) + ((size_t)(l * 2 + 1) * 8 + w) * 4096;
;     {
;         const int tr = lane >> 3, cg8 = (lane & 7) * 8;
;         const bf16_t* src = U + (size_t)(row0 + tr) * UN + 64 * w + cg8;
;         u32x4 v[8];
; #pragma unroll
;         for (int k = 0; k < 8; ++k) { v[k] = (u32x4){0u, 0u, 0u, 0u}; if (8 * k + tr < nvalid) v[k] = *(const u32x4*)(src + (size_t)(8 * k) * UN); }
; #pragma unroll
;         for (int k = 0; k < 8; ++k) *(LAS u32x4*)(xr + (8 * k + tr) * 64 + cg8) = v[k];
;     }
;     {
;         const int ch = 64 * w + lane;
;         const float* cw = a->in[11] + (size_t)l * 4 * DLRU;
;         const float cw0 = cw[ch], cw1 = cw[DLRU + ch], cw2 = cw[2 * DLRU + ch], cw3 = cw[3 * DLRU + ch], cb = a->in[12][l * DLRU + ch];
;         float xm3 = 0.f, xm2 = 0.f, xm1 = 0.f;
;         if (u.prompt) { if (u.c > 0) { xm3 = bf2f(U[(size_t)(row0 - 3) * UN + ch]); xm2 = bf2f(U[(size_t)(row0 - 2) * UN + ch]); xm1 = bf2f(U[(size_t)(row0 - 1) * UN + ch]); } }
;         else { const float* cs = a->in[3] + ((size_t)(l * NSB + u.s) * 3) * DLRU + ch; xm3 = cs[0]; xm2 = cs[DLRU]; xm1 = cs[2 * DLRU]; }
;         float* cout = out + (u.prompt ? O_CP + (size_t)(l * NB + u.b) * 3 * DLRU : O_CS + (size_t)(l * NSB + u.s) * 3 * DLRU) + ch;
;         LDS_WAIT(); asm volatile("" ::: "memory");
; #pragma unroll 8
;         for (int t = 0; t < 64; ++t) {
;             const float xv = bf2f(xr[t * 64 + lane]);
;             const float xcv = cb + cw0 * xm3 + cw1 * xm2 + cw2 * xm1 + cw3 * xv;
;             xc[t * 72 + lane] = (t < nvalid) ? f2bf(xcv) : (bf16_t)0;
;             xm3 = xm2; xm2 = xm1; xm1 = xv;
;             if (FINAL && lastc && t >= nvalid - 3 && t < nvalid) cout[(size_t)(t - (nvalid - 3)) * DLRU] = xv;
;         }
;     }
;     LDS_WAIT(); asm volatile("" ::: "memory");
.LBB0_958:
	s_or_b64 exec, exec, s[6:7]
	s_ashr_i32 s10, s8, 6
	s_load_dwordx2 s[16:17], s[2:3], 0xd8
	v_readlane_b32 s18, v255, 7
	v_readlane_b32 s19, v255, 8
	v_and_b32_e32 v96, 31, v35
	v_bfe_u32 v97, v35, 5, 1
	v_lshlrev_b32_e32 v96, 7, v96
	v_lshl_or_b32 v96, v97, 4, v96
	s_add_i32 s18, s18, s10
	s_add_i32 s19, s19, s10
	s_lshl_b32 s18, s18, 13
	s_lshl_b32 s19, s19, 13
	s_waitcnt lgkmcnt(0)
	s_add_u32 s16, s16, 0x180000
	s_addc_u32 s17, s17, 0
	s_add_u32 s20, s16, s18
	s_addc_u32 s21, s17, 0
	s_add_u32 s18, s16, s19
	s_addc_u32 s19, s17, 0
	global_load_dwordx4 v[64:67], v96, s[20:21]
	global_load_dwordx4 v[68:71], v96, s[18:19]
	global_load_dwordx4 v[72:75], v96, s[20:21] offset:32
	global_load_dwordx4 v[76:79], v96, s[18:19] offset:32
	global_load_dwordx4 v[80:83], v96, s[20:21] offset:64
	global_load_dwordx4 v[84:87], v96, s[18:19] offset:64
	global_load_dwordx4 v[88:91], v96, s[20:21] offset:96
	global_load_dwordx4 v[92:95], v96, s[18:19] offset:96
	s_lshl_b32 s6, s10, 13
	s_add_i32 s11, s6, 0
	s_add_i32 s22, s11, 0x12000
	v_lshlrev_b32_e32 v33, 7, v36
	v_add3_u32 v33, s22, v33, v144
	s_waitcnt vmcnt(0)
	ds_write_b128 v33, v[0:3]
	ds_write_b128 v33, v[8:11] offset:1024
	ds_write_b128 v33, v[4:7] offset:2048
	ds_write_b128 v33, v[16:19] offset:3072
	ds_write_b128 v33, v[12:15] offset:4096
	ds_write_b128 v33, v[24:27] offset:5120
	ds_write_b128 v33, v[20:23] offset:6144
	ds_write_b128 v33, v[28:31] offset:7168
	s_load_dwordx4 s[16:19], s[2:3], 0x58
	v_readlane_b32 s6, v255, 18
	v_and_b32_e32 v32, 63, v35
	v_readlane_b32 s7, v255, 19
	v_or_b32_e32 v4, s6, v32
	v_readlane_b32 s6, v255, 10
	v_readlane_b32 s7, v255, 11
	s_waitcnt lgkmcnt(0)
	s_add_u32 s6, s16, s6
	s_addc_u32 s7, s17, s7
	v_ashrrev_i32_e32 v5, 31, v4
	v_lshl_add_u64 v[2:3], v[4:5], 2, s[6:7]
	v_add_co_u32_e32 v8, vcc, 0x1000, v2
	v_readlane_b32 s6, v255, 0
	s_nop 0
	v_addc_co_u32_e32 v9, vcc, 0, v3, vcc
	global_load_dword v0, v[2:3], off
	global_load_dword v1, v[2:3], off offset:2048
	s_nop 0
	global_load_dword v2, v[8:9], off
	global_load_dword v3, v[8:9], off offset:2048
	v_add_u32_e32 v8, s6, v4
	v_mov_b32_e32 v6, s18
	v_mov_b32_e32 v7, s19
	v_ashrrev_i32_e32 v9, 31, v8
	v_lshl_add_u64 v[6:7], v[8:9], 2, v[6:7]
	global_load_dword v14, v[6:7], off
	v_readlane_b32 s6, v255, 16
	v_readlane_b32 s7, v255, 17
	s_mov_b64 s[8:9], -1
	s_and_b64 vcc, exec, s[6:7]
	s_cbranch_vccz .LBB0_960
	s_load_dwordx2 s[6:7], s[2:3], 0x18
	s_add_i32 s8, s0, s60
	s_mul_hi_u32 s9, s8, 0x1800
	s_mulk_i32 s8, 0x1800
	s_waitcnt lgkmcnt(0)
	s_add_u32 s6, s6, s8
	s_addc_u32 s7, s7, s9
	v_lshl_add_u64 v[8:9], v[4:5], 2, s[6:7]
	global_load_dword v6, v[8:9], off
	global_load_dword v7, v[8:9], off offset:2048
	v_add_co_u32_e32 v8, vcc, 0x1000, v8
	s_mov_b64 s[8:9], 0
	s_nop 0
	v_addc_co_u32_e32 v9, vcc, 0, v9, vcc
	global_load_dword v9, v[8:9], off

; template <bool FINAL>
; DI void lru_unit(KA a, int l, int unit, LAS unsigned char* lds) {
;     ...
;     const int taur = 16 * ((r >> 2) & 1) + 4 * (r >> 3) + (r & 3);
;     bf16x8 fa[4], fx[4];
; #pragma unroll
;     for (int ks = 0; ks < 4; ++ks) { fa[ks] = *(const bf16x8*)(WaT + r * 64 + ks * 16 + 8 * h); fx[ks] = *(const bf16x8*)(WxT + r * 64 + ks * 16 + 8 * h); }
;     ...
;                 unsigned long long* ls = (unsigned long long*)(a->ws + WS_LSUM);
;                 unsigned* lf = (unsigned*)(a->ws + WS_LFLAG);
;                 const unsigned epoch = (unsigned)l + 1u;
;                 if (u.c < NCH - 1) {
;                     const float Pt = P0 * P1 * P2 * P3, Ht = ((H0 * P1 + H1) * P2 + H2) * P3 + H3;
;                     if (h == 0) __hip_atomic_store(ls + (size_t)unit * DLRU + chn, (unsigned long long)__float_as_uint(Pt) | ((unsigned long long)__float_as_uint(Ht) << 32), __ATOMIC_RELAXED, __HIP_MEMORY_SCOPE_AGENT);
;                     asm volatile("s_waitcnt vmcnt(0)" ::: "memory");
;                     if (lane == 0) __hip_atomic_store(lf + ((size_t)unit * 8 + w) * 2 + nb, epoch, __ATOMIC_RELAXED, __HIP_MEMORY_SCOPE_AGENT);
;                 }
;                 if (u.c > 0) {
;                     {
;                         const unsigned* fp = lf + ((size_t)(u.b * NCH + (lane < u.c ? lane : 0)) * 8 + w) * 2 + nb;
;                         unsigned sp = 0;
;                         for (;;) {
;                             const bool ok = (lane >= u.c) || (__hip_atomic_load(fp, __ATOMIC_RELAXED, __HIP_MEMORY_SCOPE_AGENT) == epoch);
;                             if (__all(ok)) break;
;                             __builtin_amdgcn_s_sleep(2);
;                             if (++sp > (1u << 22)) break;
;                         }
;                     }
;                     const unsigned long long* lp = ls + (size_t)(u.b * NCH) * DLRU + chn;
;                     for (int c0 = 0; c0 < u.c; c0 += 8) {
;                         unsigned long long pv[8];
; #pragma unroll
;                         for (int k = 0; k < 8; ++k) { pv[k] = 0x3f800000ull; if (c0 + k < u.c) pv[k] = __hip_atomic_load(lp + (size_t)(c0 + k) * DLRU, __ATOMIC_RELAXED, __HIP_MEMORY_SCOPE_AGENT); }
; #pragma unroll
;                         for (int k = 0; k < 8; ++k) cin = __uint_as_float((unsigned)pv[k]) * cin + __uint_as_float((unsigned)(pv[k] >> 32));
;                     }
.Llru_conv_done:
.LBB0_1001:
	s_ashr_i32 s11, s10, 31
	v_readlane_b32 s0, v255, 7
	s_add_u32 s6, s10, s0
	s_load_dwordx4 s[24:27], s[2:3], 0xd0
	s_addc_u32 s7, s11, 0
	s_lshl_b64 s[6:7], s[6:7], 13
	v_readlane_b32 s0, v255, 8
	s_add_u32 s8, s10, s0
	s_addc_u32 s9, s11, 0
	s_lshl_b64 s[8:9], s[8:9], 13
	s_waitcnt lgkmcnt(0)
	s_mov_b64 s[30:31], s[26:27]
	s_add_u32 s0, s30, 0x180000
	s_addc_u32 s20, s31, 0
	s_add_u32 s6, s0, s6
	s_addc_u32 s7, s20, s7
	v_and_b32_e32 v124, 31, v35
	v_lshrrev_b32_e32 v8, 5, v32
	s_mov_b64 s[28:29], s[24:25]
	s_add_u32 s24, s0, s8
	v_lshrrev_b32_e32 v0, 1, v35
	v_lshlrev_b32_e32 v144, 7, v124
	s_addc_u32 s25, s20, s9
	s_waitcnt lgkmcnt(0)
	v_and_b32_e32 v7, 12, v0
	v_lshl_add_u64 v[2:3], s[6:7], 0, v[144:145]
	v_lshlrev_b32_e32 v0, 4, v8
	v_mov_b32_e32 v1, v145
	v_lshl_add_u64 v[2:3], v[2:3], 0, v[0:1]
	v_lshl_add_u64 v[4:5], s[24:25], 0, v[144:145]
	v_lshl_add_u64 v[4:5], v[4:5], 0, v[0:1]
	v_lshlrev_b32_e32 v6, 2, v35
	v_and_b32_e32 v9, 3, v35
	v_and_b32_e32 v2, 16, v6
	v_lshrrev_b32_e32 v10, 2, v32
	v_or3_b32 v9, v7, v9, v2
	v_add_u32_e32 v2, s13, v10
	v_mov_b64_e32 v[4:5], s[4:5]
	v_mad_i64_i32 v[4:5], s[4:5], v2, s64, v[4:5]
	v_readlane_b32 s4, v255, 18
	v_readlane_b32 s5, v255, 19
	s_lshl_b64 s[20:21], s[4:5], 1
	v_and_b32_e32 v11, 24, v34
	v_lshl_add_u64 v[4:5], v[4:5], 0, s[20:21]
	v_lshlrev_b32_e32 v6, 1, v11
	v_mov_b32_e32 v7, v145
	s_lshl_b64 s[4:5], s[18:19], 11
	v_lshl_add_u64 v[112:113], v[4:5], 0, v[6:7]
	v_and_b32_e32 v5, 64, v221
	v_writelane_b32 v255, s4, 20
	v_xor_b32_e32 v4, 32, v221
	v_add_u32_e32 v5, 64, v5
	v_writelane_b32 v255, s5, 21
	s_add_u32 s4, s30, 0x8000
	v_cmp_lt_i32_e32 vcc, v4, v5
	s_addc_u32 s5, s31, 0
	v_or_b32_e32 v144, 0x1000, v144
	v_cndmask_b32_e32 v4, v221, v4, vcc
	s_cmp_lt_i32 s94, 32
	v_lshlrev_b32_e32 v125, 2, v4
	v_lshl_add_u64 v[4:5], s[6:7], 0, v[144:145]
	s_cselect_b64 s[6:7], -1, 0
	v_writelane_b32 v255, s6, 22
	s_ashr_i32 s63, s62, 31
	v_lshl_add_u64 v[114:115], v[4:5], 0, v[0:1]
	v_writelane_b32 v255, s7, 23
	s_lshl_b64 s[6:7], s[62:63], 12
	s_add_u32 s0, s30, s6
	s_addc_u32 s6, s31, s7
	v_lshl_add_u64 v[4:5], s[24:25], 0, v[144:145]
	s_add_u32 s24, s0, 0x200000
	s_addc_u32 s25, s6, 0
	v_writelane_b32 v255, s24, 24
	v_cmp_eq_u32_e64 s[6:7], 0, v32
	s_mov_b32 s0, s62
	v_writelane_b32 v255, s25, 25
	v_writelane_b32 v255, s6, 26
	v_lshl_add_u64 v[116:117], v[4:5], 0, v[0:1]
	v_ashrrev_i32_e32 v3, 31, v2
	v_writelane_b32 v255, s7, 27
	v_writelane_b32 v255, s0, 28
	s_lshl_b64 s[6:7], s[62:63], 6
	v_lshlrev_b64 v[2:3], 11, v[2:3]
	v_writelane_b32 v255, s1, 29
	s_add_u32 s0, s4, s6
	s_addc_u32 s13, s5, s7
	s_lshl_b64 s[6:7], s[10:11], 3
	s_add_u32 s0, s0, s6
	v_writelane_b32 v255, s0, 30
	s_addc_u32 s0, s13, s7
	s_cmp_gt_i32 s94, 0
	v_writelane_b32 v255, s0, 31
	s_cselect_b64 s[10:11], -1, 0
	v_writelane_b32 v255, s10, 32
	v_lshl_add_u64 v[2:3], s[30:31], 0, v[2:3]
	v_lshl_add_u64 v[2:3], v[2:3], 0, s[20:21]
	v_writelane_b32 v255, s11, 33
	s_mul_i32 s10, s12, 33
	v_cmp_gt_i32_e64 s[12:13], s94, v32
	s_ashr_i32 s11, s10, 31
	s_lshl_b64 s[92:93], s[10:11], 12
	v_cndmask_b32_e64 v1, 0, v32, s[12:13]
	v_add_u32_e32 v4, s10, v1
	v_ashrrev_i32_e32 v5, 31, v4
	v_lshlrev_b64 v[4:5], 6, v[4:5]
	v_lshl_add_u64 v[4:5], s[4:5], 0, v[4:5]
	s_lshl_b64 s[4:5], s[18:19], 9
	s_add_u32 s4, s4, 0x1188000
	s_addc_u32 s5, s5, 0
	v_writelane_b32 v255, s4, 34
	v_lshl_add_u64 v[2:3], v[2:3], 0, v[6:7]
	v_or_b32_e32 v7, s94, v8
	v_writelane_b32 v255, s5, 35
	s_lshl_b64 s[4:5], s[16:17], 9
	s_add_u32 s4, s4, 0x1100000
	s_addc_u32 s5, s5, 0
	v_writelane_b32 v255, s4, 36
	s_lshl_b32 s0, s88, 7
	s_add_i32 s0, s22, s0
	v_writelane_b32 v255, s5, 37
	s_mov_b64 s[4:5], 0xaf00000
	v_lshl_add_u64 v[120:121], v[2:3], 0, s[4:5]
	v_readlane_b32 s4, v255, 14
	v_lshlrev_b32_e32 v1, 2, v124
	s_addk_i32 s0, 0xff80
	v_cmp_eq_u32_e32 vcc, 0, v7
	v_readlane_b32 s5, v255, 15
	v_lshl_add_u64 v[118:119], v[4:5], 0, s[6:7]
	v_add_u32_e32 v4, s22, v1
	v_add_u32_e32 v126, s0, v1
	v_lshl_add_u32 v1, v11, 2, s22
	s_and_b64 s[22:23], s[4:5], vcc
	s_load_dwordx4 s[4:7], s[2:3], 0xd0
	v_cmp_gt_u32_e64 s[8:9], 32, v32
	s_and_b64 s[18:19], s[14:15], s[8:9]
	v_add_u32_e32 v12, s95, v0
	v_or_b32_e32 v2, 16, v10
	s_waitcnt lgkmcnt(0)
; DI float bf2f(unsigned v) { return __uint_as_float(v << 16); }
; DI float sigmoidf_(float x) { return rcpf(1.f + __expf(-x)); }
; template <bool FINAL>
; DI void lru_unit(KA a, int l, int unit, LAS unsigned char* lds) {
;     ...
; #pragma unroll
;         for (int mb = 0; mb < 2; ++mb) {
;             float pp = 1.f, hh = 0.f;
; #pragma unroll
;             for (int i = 0; i < 16; ++i) {
;                 const int t = 32 * mb + 16 * h + i;
;                 const float rg = sigmoidf_(ar[mb][i] + ba_), ig = sigmoidf_(ai[mb][i] + bx_);
;                 const float la = c8 * rg;
;                 float av = __expf(la), mult = __builtin_amdgcn_sqrtf(fmaxf(1.f - av * av, 0.f));
;                 const float xcv = bf2f(xc[t * 72 + cl]);
;                 float bt = mult * ig * xcv;
;                 if (u.prompt && u.c == 0 && t == 0) { av = 0.f; bt = ig * xcv; }
;                 if (t >= nvalid) { av = 1.f; bt = 0.f; }
;                 hh = av * hh + bt; pp *= av;
;                 ar[mb][i] = pp; ai[mb][i] = hh;
;             }
;         }
	s_add_u32 s0, s6, s92
	s_addc_u32 s4, s7, s93
	s_add_u32 s6, s0, 0x207000
	v_or_b32_e32 v3, 32, v10
	v_or_b32_e32 v5, 48, v10
	v_mul_u32_u24_e32 v6, 0x90, v9
	v_cmp_gt_u32_e64 s[24:25], s88, v0
	v_or_b32_e32 v7, 1, v0
	v_or_b32_e32 v9, 2, v0
	v_or_b32_e32 v11, 3, v0
	v_or_b32_e32 v13, 4, v0
	v_or_b32_e32 v14, 5, v0
	v_or_b32_e32 v15, 6, v0
	v_or_b32_e32 v16, 7, v0
	v_or_b32_e32 v17, 8, v0
	v_or_b32_e32 v18, 9, v0
	v_or_b32_e32 v19, 10, v0
	v_or_b32_e32 v20, 11, v0
	v_or_b32_e32 v21, 12, v0
	v_or_b32_e32 v22, 13, v0
	v_or_b32_e32 v23, 14, v0
	v_or_b32_e32 v24, 15, v0
	v_or_b32_e32 v25, 32, v0
	v_or_b32_e32 v26, 33, v0
	v_or_b32_e32 v27, 34, v0
	v_or_b32_e32 v28, 35, v0
	v_or_b32_e32 v29, 36, v0
	v_or_b32_e32 v30, 37, v0
	v_or_b32_e32 v31, 38, v0
	v_or_b32_e32 v32, 39, v0
	v_or_b32_e32 v33, 40, v0
	v_or_b32_e32 v34, 41, v0
	v_or_b32_e32 v35, 42, v0
	v_or_b32_e32 v36, 43, v0
	v_or_b32_e32 v37, 44, v0
	v_or_b32_e32 v38, 45, v0
	v_or_b32_e32 v39, 46, v0
	v_or_b32_e32 v0, 47, v0
	s_addc_u32 s7, s4, 0
	v_cmp_gt_u32_e64 s[14:15], s88, v10
	v_cmp_gt_u32_e64 s[10:11], s88, v2
	v_cmp_gt_u32_e64 s[96:97], s88, v3
	v_cmp_gt_u32_e64 s[20:21], s88, v5
	v_mul_u32_u24_e32 v127, 0x900, v8
	v_mul_u32_u24_e32 v128, 0x90, v7
	v_cmp_gt_u32_e64 s[26:27], s88, v7
	v_cmp_gt_u32_e64 s[28:29], s88, v9
	v_cmp_gt_u32_e64 s[30:31], s88, v11
	v_cmp_gt_u32_e64 s[34:35], s88, v13
	v_cmp_gt_u32_e64 s[36:37], s88, v14
	v_cmp_gt_u32_e64 s[38:39], s88, v15
	v_cmp_gt_u32_e64 s[40:41], s88, v16
	v_cmp_gt_u32_e64 s[42:43], s88, v17
	v_cmp_gt_u32_e64 s[44:45], s88, v18
	v_cmp_gt_u32_e64 s[46:47], s88, v19
	v_cmp_gt_u32_e64 s[48:49], s88, v20
	v_cmp_gt_u32_e64 s[50:51], s88, v21
	v_cmp_gt_u32_e64 s[52:53], s88, v22
	v_cmp_gt_u32_e64 s[54:55], s88, v23
	v_cmp_gt_u32_e64 s[56:57], s88, v24
	v_cmp_gt_u32_e64 s[58:59], s88, v25
	v_cmp_gt_u32_e64 s[60:61], s88, v26
	v_cmp_gt_u32_e64 s[62:63], s88, v27
	v_cmp_gt_u32_e64 s[64:65], s88, v28
	v_cmp_gt_u32_e64 s[66:67], s88, v29
	v_cmp_gt_u32_e64 s[68:69], s88, v30
	v_cmp_gt_u32_e64 s[70:71], s88, v31
	v_cmp_gt_u32_e64 s[72:73], s88, v32
	v_cmp_gt_u32_e64 s[74:75], s88, v33
	v_cmp_gt_u32_e64 s[76:77], s88, v34
	v_cmp_gt_u32_e64 s[78:79], s88, v35
	v_cmp_gt_u32_e64 s[80:81], s88, v36
	v_cmp_gt_u32_e64 s[82:83], s88, v37
	v_cmp_gt_u32_e64 s[84:85], s88, v38
	v_cmp_gt_u32_e64 s[86:87], s88, v39
	v_cmp_gt_u32_e64 s[88:89], s88, v0
	v_lshlrev_b32_e32 v8, 11, v8
	v_lshlrev_b32_e32 v7, 7, v7
	v_lshlrev_b32_e32 v9, 7, v9
	v_lshlrev_b32_e32 v11, 7, v11
	v_lshlrev_b32_e32 v13, 7, v13
	v_lshlrev_b32_e32 v14, 7, v14
	v_lshlrev_b32_e32 v15, 7, v15
	v_lshlrev_b32_e32 v16, 7, v16
	v_lshlrev_b32_e32 v17, 7, v17
	v_lshlrev_b32_e32 v18, 7, v18
	v_lshlrev_b32_e32 v19, 7, v19
	v_lshlrev_b32_e32 v20, 7, v20
	v_lshlrev_b32_e32 v21, 7, v21
	v_lshlrev_b32_e32 v22, 7, v22
	v_lshlrev_b32_e32 v23, 7, v23
	v_lshlrev_b32_e32 v24, 7, v24
	v_lshlrev_b32_e32 v25, 7, v25
	v_lshlrev_b32_e32 v26, 7, v26
	v_lshlrev_b32_e32 v27, 7, v27
	v_lshlrev_b32_e32 v28, 7, v28
	v_lshlrev_b32_e32 v29, 7, v29
	v_lshlrev_b32_e32 v30, 7, v30
	v_lshlrev_b32_e32 v31, 7, v31
	v_lshlrev_b32_e32 v32, 7, v32
	v_lshlrev_b32_e32 v33, 7, v33
	v_lshlrev_b32_e32 v34, 7, v34
	v_lshlrev_b32_e32 v35, 7, v35
	v_lshlrev_b32_e32 v36, 7, v36
	v_lshlrev_b32_e32 v37, 7, v37
	v_lshlrev_b32_e32 v38, 7, v38
	v_lshlrev_b32_e32 v39, 7, v39
	v_lshlrev_b32_e32 v0, 7, v0
	v_lshlrev_b32_e32 v10, 7, v10
	v_lshlrev_b32_e32 v2, 7, v2
	v_lshlrev_b32_e32 v3, 7, v3
	v_lshlrev_b32_e32 v5, 7, v5
	v_writelane_b32 v255, s6, 38
	s_mov_b32 s90, 0
	s_mov_b64 s[92:93], -1
	v_writelane_b32 v255, s7, 39
	v_add_u32_e32 v129, v12, v6
	v_add_u32_e32 v130, v4, v8
	v_add_u32_e32 v131, v4, v7
	v_add_u32_e32 v132, v4, v9
	v_add_u32_e32 v133, v4, v11
	v_add_u32_e32 v134, v4, v13
	v_add_u32_e32 v135, v4, v14
	v_add_u32_e32 v136, v4, v15
	v_add_u32_e32 v137, v4, v16
	v_add_u32_e32 v138, v4, v17
	v_add_u32_e32 v139, v4, v18
	v_add_u32_e32 v140, v4, v19
	v_add_u32_e32 v141, v4, v20
	v_add_u32_e32 v142, v4, v21
	v_add_u32_e32 v143, v4, v22
	v_add_u32_e32 v144, v4, v23
	v_add_u32_e32 v154, v4, v24
	v_add_u32_e32 v155, v4, v25
	v_add_u32_e32 v156, v4, v26
	v_add_u32_e32 v157, v4, v27
	v_add_u32_e32 v158, v4, v28
	v_add_u32_e32 v159, v4, v29
	v_add_u32_e32 v160, v4, v30
	v_add_u32_e32 v161, v4, v31
	v_add_u32_e32 v162, v4, v32
	v_add_u32_e32 v163, v4, v33
	v_add_u32_e32 v164, v4, v34
	v_add_u32_e32 v165, v4, v35
	v_add_u32_e32 v166, v4, v36
	v_add_u32_e32 v167, v4, v37
	v_add_u32_e32 v168, v4, v38
	v_add_u32_e32 v169, v4, v39
	v_add_u32_e32 v170, v4, v0
	v_add_u32_e32 v171, v1, v10
	v_add_u32_e32 v172, v1, v2
	v_add_u32_e32 v173, v1, v3
	v_add_u32_e32 v174, v1, v5
	s_branch .LBB0_1003

; template <bool FINAL>
; DI void lru_unit(KA a, int l, int unit, LAS unsigned char* lds) {
;     ...
;         const int cl = 32 * nb + r, chn = 64 * w + cl;
;         const float ba_ = a->in[14][l * DLRU + chn], bx_ = a->in[16][l * DLRU + chn];
;         const float c8 = -8.f * log1pf(__expf(-a->in[17][l * DLRU + chn]));
;         float cin = 0.f;
;         if (FINAL && !u.prompt) cin = a->in[2][(size_t)(l * NSB + u.s) * DLRU + chn];
.LBB0_1003:
	s_lshl_b32 s0, s90, 5
	v_readlane_b32 s4, v255, 18
	v_readlane_b32 s5, v255, 0
	v_or_b32_e32 v192, s0, v124
	s_nop 1
	v_or_b32_e32 v192, s4, v192
	v_add_u32_e32 v188, s5, v192
	v_ashrrev_i32_e32 v193, 31, v192
	v_ashrrev_i32_e32 v189, 31, v188
	s_load_dwordx2 s[4:5], s[2:3], 0x70
	v_lshlrev_b64 v[188:189], 2, v[188:189]
	s_waitcnt lgkmcnt(0)
	v_lshl_add_u64 v[190:191], s[4:5], 0, v[188:189]
	s_load_dwordx4 s[4:7], s[2:3], 0x80
	global_load_dword v184, v[190:191], off
	s_waitcnt lgkmcnt(0)
	v_lshl_add_u64 v[190:191], s[4:5], 0, v[188:189]
	global_load_dword v185, v[190:191], off
	v_lshl_add_u64 v[190:191], s[6:7], 0, v[188:189]
	global_load_dword v186, v[190:191], off
	v_mov_b32_e32 v187, 0
	v_readlane_b32 s4, v255, 16
	v_readlane_b32 s5, v255, 17
	s_andn2_b64 vcc, exec, s[4:5]
	s_cbranch_vccnz .Llru_hb_skip
	s_load_dwordx2 s[4:5], s[2:3], 0x10
	v_readlane_b32 s6, v255, 20
	v_readlane_b32 s7, v255, 21
	s_waitcnt lgkmcnt(0)
	s_add_u32 s4, s4, s6
	s_addc_u32 s5, s5, s7
	v_lshl_add_u64 v[190:191], v[192:193], 2, s[4:5]
	global_load_dword v187, v[190:191], off

; DI float bf2f(unsigned v) { return __uint_as_float(v << 16); }
; DI float sigmoidf_(float x) { return rcpf(1.f + __expf(-x)); }
; template <bool FINAL>
; DI void lru_unit(KA a, int l, int unit, LAS unsigned char* lds) {
;     ...
;         const int cl = 32 * nb + r, chn = 64 * w + cl;
;         const float ba_ = a->in[14][l * DLRU + chn], bx_ = a->in[16][l * DLRU + chn];
;         const float c8 = -8.f * log1pf(__expf(-a->in[17][l * DLRU + chn]));
;         float cin = 0.f;
;         if (FINAL && !u.prompt) cin = a->in[2][(size_t)(l * NSB + u.s) * DLRU + chn];
; #pragma unroll
;         for (int mb = 0; mb < 2; ++mb) {
;             float pp = 1.f, hh = 0.f;
; #pragma unroll
;             for (int i = 0; i < 16; ++i) {
;                 const int t = 32 * mb + 16 * h + i;
;                 const float rg = sigmoidf_(ar[mb][i] + ba_), ig = sigmoidf_(ai[mb][i] + bx_);
;                 const float la = c8 * rg;
;                 float av = __expf(la), mult = __builtin_amdgcn_sqrtf(fmaxf(1.f - av * av, 0.f));
;                 const float xcv = bf2f(xc[t * 72 + cl]);
;                 float bt = mult * ig * xcv;
;                 if (u.prompt && u.c == 0 && t == 0) { av = 0.f; bt = ig * xcv; }
;                 if (t >= nvalid) { av = 1.f; bt = 0.f; }
;                 hh = av * hh + bt; pp *= av;
;                 ar[mb][i] = pp; ai[mb][i] = hh;
;             }
;         }
.LBB0_1013:
	s_lshl_b32 s0, s90, 5
	v_or_b32_e32 v179, s0, v124
	v_readlane_b32 s4, v255, 18
	v_readlane_b32 s5, v255, 19
	v_mov_b32_e32 v175, v187
	v_or_b32_e32 v122, s4, v179
	v_ashrrev_i32_e32 v123, 31, v122
	v_mov_b32_e32 v177, v184
	v_mov_b32_e32 v176, v185
	v_mov_b32_e32 v178, v186
.LBB0_1015:
	v_mul_f32_e32 v178, 0xbfb8aa3b, v178
	v_exp_f32_e32 v178, v178
	s_mov_b32 s4, 0x3f2aaaab
	v_add_f32_e32 v48, v48, v177
	v_mul_f32_e32 v48, 0xbfb8aa3b, v48
	v_add_f32_e32 v182, 1.0, v178
	v_frexp_mant_f32_e32 v184, v182
	v_cvt_f64_f32_e32 v[180:181], v182
	v_add_f32_e32 v183, -1.0, v182
	v_frexp_exp_i32_f64_e32 v180, v[180:181]
	v_cmp_gt_f32_e32 vcc, s4, v184
	v_sub_f32_e32 v185, v183, v182
	v_sub_f32_e32 v183, v178, v183
	v_subbrev_co_u32_e32 v180, vcc, 0, v180, vcc
	v_add_f32_e32 v185, 1.0, v185
	v_sub_u32_e32 v181, 0, v180
	v_add_f32_e32 v183, v183, v185
	v_ldexp_f32 v182, v182, v181
	v_ldexp_f32 v181, v183, v181
	v_add_f32_e32 v183, -1.0, v182
	v_add_f32_e32 v186, 1.0, v182
	v_add_f32_e32 v184, 1.0, v183
	v_add_f32_e32 v187, -1.0, v186
	v_sub_f32_e32 v184, v182, v184
	v_sub_f32_e32 v182, v182, v187
	v_add_f32_e32 v184, v181, v184
	v_add_f32_e32 v181, v181, v182
	v_add_f32_e32 v182, v186, v181
	v_rcp_f32_e32 v187, v182
	v_add_f32_e32 v185, v183, v184
	v_sub_f32_e32 v183, v185, v183
	v_sub_f32_e32 v183, v184, v183
	v_sub_f32_e32 v184, v182, v186
	v_sub_f32_e32 v181, v181, v184
	v_mul_f32_e32 v184, v185, v187
	v_mul_f32_e32 v186, v182, v184
	v_fma_f32 v188, v184, v182, -v186
	v_fmac_f32_e32 v188, v184, v181
	v_add_f32_e32 v189, v186, v188
	v_sub_f32_e32 v190, v185, v189
	v_sub_f32_e32 v185, v185, v190
	v_sub_f32_e32 v186, v189, v186
	v_sub_f32_e32 v185, v185, v189
	v_add_f32_e32 v183, v183, v185
	v_sub_f32_e32 v185, v186, v188
	v_add_f32_e32 v183, v185, v183
	v_add_f32_e32 v185, v190, v183
	v_mul_f32_e32 v186, v187, v185
	v_mul_f32_e32 v188, v182, v186
	v_fma_f32 v182, v186, v182, -v188
	v_fmac_f32_e32 v182, v186, v181
	v_sub_f32_e32 v181, v190, v185
	v_add_f32_e32 v181, v183, v181
	v_add_f32_e32 v183, v188, v182
	v_sub_f32_e32 v189, v185, v183
	v_sub_f32_e32 v185, v185, v189
	v_sub_f32_e32 v188, v183, v188
	v_sub_f32_e32 v183, v185, v183
	v_add_f32_e32 v181, v181, v183
	v_sub_f32_e32 v182, v188, v182
	v_cvt_f32_i32_e32 v180, v180
	v_add_f32_e32 v181, v182, v181
	v_add_f32_e32 v182, v184, v186
	v_add_f32_e32 v181, v189, v181
	v_sub_f32_e32 v183, v182, v184
	v_mul_f32_e32 v181, v187, v181
	v_sub_f32_e32 v183, v186, v183
	v_add_f32_e32 v181, v183, v181
	v_mul_f32_e32 v186, 0x3f317218, v180
	s_mov_b32 s4, 0x3f317218
	v_add_f32_e32 v183, v182, v181
	v_fma_f32 v187, v180, s4, -v186
	v_mul_f32_e32 v184, v183, v183
	v_mov_b32_e32 v185, 0x3ecc95a3
	v_fmac_f32_e32 v187, 0xb102e308, v180
	v_sub_f32_e32 v180, v183, v182
	v_fmamk_f32 v185, v184, 0x3e9b6dac, v185
	v_sub_f32_e32 v180, v181, v180
	v_add_f32_e32 v181, v186, v187
	v_fmaak_f32 v185, v184, v185, 0x3f2aaada
	v_sub_f32_e32 v182, v181, v186
	v_ldexp_f32 v186, v183, 1
	v_mul_f32_e32 v183, v183, v184
	v_mul_f32_e32 v183, v183, v185
	v_add_f32_e32 v184, v186, v183
	v_sub_f32_e32 v185, v184, v186
	v_ldexp_f32 v180, v180, 1
	v_sub_f32_e32 v183, v183, v185
	v_add_f32_e32 v180, v180, v183
	v_add_f32_e32 v183, v184, v180
	v_sub_f32_e32 v184, v183, v184
	v_sub_f32_e32 v180, v180, v184
	v_add_f32_e32 v184, v181, v183
	v_sub_f32_e32 v185, v184, v181
	v_sub_f32_e32 v186, v184, v185
	v_sub_f32_e32 v182, v187, v182
	v_sub_f32_e32 v181, v181, v186
	v_sub_f32_e32 v183, v183, v185
	v_add_f32_e32 v181, v183, v181
	v_add_f32_e32 v183, v182, v180
	v_sub_f32_e32 v185, v183, v182
	v_sub_f32_e32 v186, v183, v185
	v_sub_f32_e32 v182, v182, v186
	v_sub_f32_e32 v180, v180, v185
	v_add_f32_e32 v181, v183, v181
	v_add_f32_e32 v180, v180, v182
	v_add_f32_e32 v182, v184, v181
	v_sub_f32_e32 v183, v182, v184
	v_exp_f32_e32 v48, v48
	v_sub_f32_e32 v181, v181, v183
	v_add_f32_e32 v180, v180, v181
	s_mov_b32 s4, 0x7f800000
	v_add_f32_e32 v180, v182, v180
	v_cmp_neq_f32_e32 vcc, s4, v178
	v_add_f32_e32 v48, 1.0, v48
	s_mov_b32 s4, 0x33800000
	v_cndmask_b32_e32 v180, v230, v180, vcc
	v_cmp_ngt_f32_e32 vcc, -1.0, v178
	v_rcp_f32_e32 v48, v48
	v_add_f32_e32 v49, v49, v177
	v_cndmask_b32_e32 v180, v231, v180, vcc
	v_cmp_neq_f32_e32 vcc, -1.0, v178
	v_mul_f32_e32 v49, 0xbfb8aa3b, v49
	v_exp_f32_e32 v49, v49
	v_cndmask_b32_e32 v180, v232, v180, vcc
	v_cmp_lt_f32_e64 vcc, |v178|, s4
	v_add_f32_e32 v32, v32, v176
	v_mul_f32_e32 v32, 0xbfb8aa3b, v32
	v_cndmask_b32_e32 v178, v180, v178, vcc
	v_mul_f32_e32 v178, 0xc1000000, v178
	v_mul_f32_e32 v48, v48, v178
	v_mul_f32_e32 v48, 0x3fb8aa3b, v48
	v_exp_f32_e32 v48, v48
	v_add_f32_e32 v49, 1.0, v49
	v_exp_f32_e32 v32, v32
	v_rcp_f32_e32 v49, v49
	v_fma_f32 v180, -v48, v48, 1.0
	v_add_f32_e32 v33, v33, v176
	v_add_f32_e32 v32, 1.0, v32
	v_max_f32_e32 v180, 0, v180
	v_mul_f32_e32 v33, 0xbfb8aa3b, v33
	v_mul_f32_e32 v49, v49, v178
	v_rcp_f32_e32 v32, v32
	v_sqrt_f32_e32 v180, v180
	v_exp_f32_e32 v33, v33
	v_mul_f32_e32 v49, 0x3fb8aa3b, v49
	v_exp_f32_e32 v49, v49
	v_add_f32_e32 v50, v50, v177
	v_mul_f32_e32 v50, 0xbfb8aa3b, v50
	v_lshl_add_u32 v179, v179, 1, s95
	v_exp_f32_e32 v50, v50
	v_add_u32_e32 v181, v179, v127
	v_mul_f32_e32 v180, v32, v180
	v_add_f32_e32 v33, 1.0, v33
	v_add_u32_e32 v179, v179, v128
	ds_read_u16 v181, v181
	ds_read_u16 v182, v179
	ds_read_u16 v183, v179 offset:144
	ds_read_u16 v184, v179 offset:288
	ds_read_u16 v185, v179 offset:432
	ds_read_u16 v186, v179 offset:576
	ds_read_u16 v187, v179 offset:720
	ds_read_u16 v188, v179 offset:864
	v_cndmask_b32_e64 v32, v180, v32, s[22:23]
	v_rcp_f32_e32 v180, v33
	v_fma_f32 v33, -v49, v49, 1.0
	s_waitcnt lgkmcnt(7)
; DI float bf2f(unsigned v) { return __uint_as_float(v << 16); }
; DI float sigmoidf_(float x) { return rcpf(1.f + __expf(-x)); }
; template <bool FINAL>
; DI void lru_unit(KA a, int l, int unit, LAS unsigned char* lds) {
;     ...
; #pragma unroll
;         for (int mb = 0; mb < 2; ++mb) {
;             float pp = 1.f, hh = 0.f;
; #pragma unroll
;             for (int i = 0; i < 16; ++i) {
;                 const int t = 32 * mb + 16 * h + i;
;                 const float rg = sigmoidf_(ar[mb][i] + ba_), ig = sigmoidf_(ai[mb][i] + bx_);
;                 const float la = c8 * rg;
;                 float av = __expf(la), mult = __builtin_amdgcn_sqrtf(fmaxf(1.f - av * av, 0.f));
;                 const float xcv = bf2f(xc[t * 72 + cl]);
;                 float bt = mult * ig * xcv;
;                 if (u.prompt && u.c == 0 && t == 0) { av = 0.f; bt = ig * xcv; }
;                 if (t >= nvalid) { av = 1.f; bt = 0.f; }
;                 hh = av * hh + bt; pp *= av;
;                 ar[mb][i] = pp; ai[mb][i] = hh;
;             }
;         }
	v_lshlrev_b32_e32 v181, 16, v181
	v_max_f32_e32 v33, 0, v33
	v_mul_f32_e32 v32, v32, v181
	v_sqrt_f32_e32 v181, v33
	v_add_f32_e32 v50, 1.0, v50
	v_add_f32_e32 v51, v51, v177
	v_rcp_f32_e32 v50, v50
	v_mul_f32_e32 v51, 0xbfb8aa3b, v51
	v_exp_f32_e32 v51, v51
	v_cndmask_b32_e64 v48, v48, 0, s[22:23]
	v_add_f32_e32 v34, v34, v176
	v_cndmask_b32_e64 v33, 1.0, v48, s[24:25]
	s_waitcnt lgkmcnt(6)
	v_lshlrev_b32_e32 v48, 16, v182
	v_mul_f32_e32 v180, v180, v181
	v_mul_f32_e32 v34, 0xbfb8aa3b, v34
	v_mul_f32_e32 v48, v180, v48
	v_exp_f32_e32 v180, v34
	v_mul_f32_e32 v34, v50, v178
	v_mul_f32_e32 v34, 0x3fb8aa3b, v34
	v_add_f32_e32 v51, 1.0, v51
	v_exp_f32_e32 v50, v34
	v_rcp_f32_e32 v51, v51
	v_cndmask_b32_e64 v32, 0, v32, s[24:25]
	v_fmac_f32_e32 v32, 0, v33
	v_cndmask_b32_e64 v48, 0, v48, s[26:27]
	v_cndmask_b32_e64 v49, 1.0, v49, s[26:27]
	v_add_f32_e32 v35, v35, v176
	v_fmac_f32_e32 v48, v49, v32
	v_mul_f32_e32 v34, v49, v33
	v_add_f32_e32 v49, 1.0, v180
	v_fma_f32 v180, -v50, v50, 1.0
	v_mul_f32_e32 v35, 0xbfb8aa3b, v35
	v_mul_f32_e32 v51, v51, v178
	v_max_f32_e32 v180, 0, v180
	v_exp_f32_e32 v35, v35
	v_mul_f32_e32 v51, 0x3fb8aa3b, v51
	v_rcp_f32_e32 v49, v49
	v_sqrt_f32_e32 v180, v180
	v_exp_f32_e32 v51, v51
	v_add_f32_e32 v52, v52, v177
	v_mul_f32_e32 v52, 0xbfb8aa3b, v52
	v_exp_f32_e32 v52, v52
	v_add_f32_e32 v35, 1.0, v35
	v_mul_f32_e32 v49, v49, v180
	v_rcp_f32_e32 v180, v35
	v_fma_f32 v35, -v51, v51, 1.0
	s_waitcnt lgkmcnt(5)
	v_lshlrev_b32_e32 v181, 16, v183
	v_max_f32_e32 v35, 0, v35
	v_mul_f32_e32 v49, v49, v181
	v_sqrt_f32_e32 v181, v35
	v_add_f32_e32 v52, 1.0, v52
	v_add_f32_e32 v53, v53, v177
	v_rcp_f32_e32 v52, v52
	v_mul_f32_e32 v53, 0xbfb8aa3b, v53
	v_exp_f32_e32 v53, v53
	v_cndmask_b32_e64 v49, 0, v49, s[28:29]
	v_cndmask_b32_e64 v50, 1.0, v50, s[28:29]
	v_add_f32_e32 v36, v36, v176
	v_fmac_f32_e32 v49, v50, v48
	v_mul_f32_e32 v35, v50, v34
	s_waitcnt lgkmcnt(4)
	v_lshlrev_b32_e32 v50, 16, v184
	v_mul_f32_e32 v180, v180, v181
	v_mul_f32_e32 v36, 0xbfb8aa3b, v36
	v_mul_f32_e32 v50, v180, v50
	v_exp_f32_e32 v180, v36
	v_mul_f32_e32 v36, v52, v178
	v_mul_f32_e32 v36, 0x3fb8aa3b, v36
	v_add_f32_e32 v53, 1.0, v53
	v_exp_f32_e32 v52, v36
	v_rcp_f32_e32 v53, v53
	v_cndmask_b32_e64 v50, 0, v50, s[30:31]
	v_cndmask_b32_e64 v51, 1.0, v51, s[30:31]
	v_add_f32_e32 v37, v37, v176
	v_fmac_f32_e32 v50, v51, v49
	v_mul_f32_e32 v36, v51, v35
	v_add_f32_e32 v51, 1.0, v180
	v_fma_f32 v180, -v52, v52, 1.0
	v_mul_f32_e32 v37, 0xbfb8aa3b, v37
	v_mul_f32_e32 v53, v53, v178
	v_max_f32_e32 v180, 0, v180
	v_exp_f32_e32 v37, v37
	v_mul_f32_e32 v53, 0x3fb8aa3b, v53
	v_rcp_f32_e32 v51, v51
	v_sqrt_f32_e32 v180, v180
	v_exp_f32_e32 v53, v53
	v_add_f32_e32 v54, v54, v177
	v_mul_f32_e32 v54, 0xbfb8aa3b, v54
	v_exp_f32_e32 v54, v54
	v_add_f32_e32 v37, 1.0, v37
	v_mul_f32_e32 v51, v51, v180
	v_rcp_f32_e32 v180, v37
	v_fma_f32 v37, -v53, v53, 1.0
	s_waitcnt lgkmcnt(3)
	v_lshlrev_b32_e32 v181, 16, v185
	v_max_f32_e32 v37, 0, v37
	v_mul_f32_e32 v51, v51, v181
	v_sqrt_f32_e32 v181, v37
	v_add_f32_e32 v54, 1.0, v54
	v_add_f32_e32 v55, v55, v177
	v_rcp_f32_e32 v54, v54
	v_mul_f32_e32 v55, 0xbfb8aa3b, v55
	v_exp_f32_e32 v55, v55
	v_cndmask_b32_e64 v51, 0, v51, s[34:35]
	v_cndmask_b32_e64 v52, 1.0, v52, s[34:35]
	v_add_f32_e32 v38, v38, v176
	v_fmac_f32_e32 v51, v52, v50
	v_mul_f32_e32 v37, v52, v36
	s_waitcnt lgkmcnt(2)
	v_lshlrev_b32_e32 v52, 16, v186
	v_mul_f32_e32 v180, v180, v181
	v_mul_f32_e32 v38, 0xbfb8aa3b, v38
	v_mul_f32_e32 v52, v180, v52
	v_exp_f32_e32 v180, v38
	v_mul_f32_e32 v38, v54, v178
	v_mul_f32_e32 v38, 0x3fb8aa3b, v38
	v_add_f32_e32 v55, 1.0, v55
	v_exp_f32_e32 v54, v38
	v_rcp_f32_e32 v55, v55
	v_cndmask_b32_e64 v52, 0, v52, s[36:37]
	v_cndmask_b32_e64 v53, 1.0, v53, s[36:37]
	v_add_f32_e32 v39, v39, v176
	v_fmac_f32_e32 v52, v53, v51
	v_mul_f32_e32 v38, v53, v37
	v_add_f32_e32 v53, 1.0, v180
	v_fma_f32 v180, -v54, v54, 1.0
	v_mul_f32_e32 v39, 0xbfb8aa3b, v39
	v_mul_f32_e32 v55, v55, v178
	v_max_f32_e32 v180, 0, v180
	v_exp_f32_e32 v39, v39
	v_mul_f32_e32 v55, 0x3fb8aa3b, v55
	v_rcp_f32_e32 v53, v53
	v_sqrt_f32_e32 v180, v180
	v_exp_f32_e32 v55, v55
	v_add_f32_e32 v56, v56, v177
	v_mul_f32_e32 v56, 0xbfb8aa3b, v56
	v_exp_f32_e32 v56, v56
	v_add_f32_e32 v39, 1.0, v39
	v_mul_f32_e32 v53, v53, v180
	v_rcp_f32_e32 v180, v39
	v_fma_f32 v39, -v55, v55, 1.0
	s_waitcnt lgkmcnt(1)
	v_lshlrev_b32_e32 v181, 16, v187
	v_max_f32_e32 v39, 0, v39
	v_mul_f32_e32 v53, v53, v181
	v_sqrt_f32_e32 v181, v39
	v_add_f32_e32 v56, 1.0, v56
	v_add_f32_e32 v57, v57, v177
	v_rcp_f32_e32 v56, v56
	v_mul_f32_e32 v57, 0xbfb8aa3b, v57
	v_exp_f32_e32 v57, v57
	v_cndmask_b32_e64 v53, 0, v53, s[38:39]
	v_cndmask_b32_e64 v54, 1.0, v54, s[38:39]
	v_add_f32_e32 v40, v40, v176
	v_fmac_f32_e32 v53, v54, v52
	v_mul_f32_e32 v39, v54, v38
	s_waitcnt lgkmcnt(0)
	v_lshlrev_b32_e32 v54, 16, v188
	v_mul_f32_e32 v180, v180, v181
	v_mul_f32_e32 v40, 0xbfb8aa3b, v40
	v_mul_f32_e32 v54, v180, v54
	v_exp_f32_e32 v180, v40
	v_mul_f32_e32 v40, v56, v178
	v_mul_f32_e32 v40, 0x3fb8aa3b, v40
	v_add_f32_e32 v57, 1.0, v57
	v_exp_f32_e32 v56, v40
	v_rcp_f32_e32 v57, v57
	v_cndmask_b32_e64 v54, 0, v54, s[40:41]
	v_cndmask_b32_e64 v55, 1.0, v55, s[40:41]
	v_add_f32_e32 v41, v41, v176
	v_fmac_f32_e32 v54, v55, v53
	v_mul_f32_e32 v40, v55, v39
	v_readlane_b32 s4, v255, 14
	v_readlane_b32 s5, v255, 15
	s_and_b64 vcc, exec, s[4:5]
	s_cbranch_vccnz .Llru_scan_cont
	s_waitcnt lgkmcnt(0)
	v_mov_b32_e32 v55, v54
	v_mov_b32_e32 v41, v40
	v_mov_b32_e32 v56, v54
	v_mov_b32_e32 v42, v40
	v_mov_b32_e32 v57, v54
	v_mov_b32_e32 v43, v40
	v_mov_b32_e32 v58, v54
	v_mov_b32_e32 v44, v40
	v_mov_b32_e32 v59, v54
	v_mov_b32_e32 v45, v40
	v_mov_b32_e32 v60, v54
	v_mov_b32_e32 v46, v40
	v_mov_b32_e32 v61, v54
	v_mov_b32_e32 v47, v40
	v_mov_b32_e32 v62, v54
	v_mov_b32_e32 v63, v40
	v_mov_b32_e32 v180, 0
	v_mov_b32_e32 v181, 1.0
	v_mov_b32_e32 v18, 0
	v_mov_b32_e32 v182, 1.0
	v_mov_b32_e32 v19, 0
	v_mov_b32_e32 v183, 1.0
	v_mov_b32_e32 v20, 0
	v_mov_b32_e32 v184, 1.0
	v_mov_b32_e32 v21, 0
	v_mov_b32_e32 v185, 1.0
	v_mov_b32_e32 v22, 0
	v_mov_b32_e32 v186, 1.0
	v_mov_b32_e32 v23, 0
	v_mov_b32_e32 v187, 1.0
	v_mov_b32_e32 v24, 0
	v_mov_b32_e32 v188, 1.0
	v_mov_b32_e32 v25, 0
	v_mov_b32_e32 v179, 1.0
	v_mov_b32_e32 v26, 0
	v_mov_b32_e32 v189, 1.0
	v_mov_b32_e32 v27, 0
	v_mov_b32_e32 v190, 1.0
	v_mov_b32_e32 v28, 0
	v_mov_b32_e32 v191, 1.0
	v_mov_b32_e32 v29, 0
	v_mov_b32_e32 v192, 1.0
	v_mov_b32_e32 v30, 0
	v_mov_b32_e32 v193, 1.0
	v_mov_b32_e32 v31, 0
	v_mov_b32_e32 v176, 1.0
	v_mov_b32_e32 v177, 0
	v_mov_b32_e32 v178, 1.0
	s_branch .Llru_scan_end
